# prep: masked-score MFMA chain reads pipelined 5 pairs deep (on top of row-loop specialization, natural-pair dot product, log fixup removal; scan as before)
# baseline (speedup 1.0000x reference)
; #define LAS __attribute__((address_space(3)))
; __device__ __forceinline__ void gla_prep_phase(const Ctx& c, int j, LAS unsigned char* lds) {
;     ...
; #pragma unroll
;         for (int jj = 0; jj < 4; ++jj) { const int idx = c.tid + 512 * jj, i = idx >> 5, c16 = idx & 31;
;             *(u32x4*)(qdst + i * 256 + c16 * 8) = *(const LAS u32x4*)(QL + i * 528 + c16 * 16); }
;         if (wid < 4) {
.LBB0_678:
	s_or_b64 exec, exec, s[0:1]
	s_lshl_b64 s[0:1], s[94:95], 14
	v_add_u32_e32 v0, v121, v133
	s_lshl_b64 s[0:1], s[0:1], 1
	s_waitcnt lgkmcnt(0)
	s_barrier
	ds_read_b128 v[0:3], v0 offset:6144
	s_add_u32 s0, s77, s0
	s_addc_u32 s1, s78, s1
	v_lshl_add_u64 v[4:5], v[96:97], 1, s[0:1]
	v_mov_b32_e32 v105, v16
	v_lshl_add_u64 v[4:5], v[4:5], 0, v[104:105]
	s_waitcnt lgkmcnt(0)
	global_store_dwordx4 v[4:5], v[0:3], off
	v_lshl_add_u64 v[4:5], v[98:99], 1, s[0:1]
	v_lshl_add_u64 v[4:5], v[4:5], 0, v[104:105]
	v_add_u32_e32 v0, v123, v133
	ds_read_b128 v[0:3], v0 offset:6144
	s_andn2_b64 vcc, exec, s[90:91]
	s_waitcnt lgkmcnt(0)
	global_store_dwordx4 v[4:5], v[0:3], off
	s_nop 1
	v_add_u32_e32 v0, v125, v133
	ds_read_b128 v[0:3], v0 offset:6144
	v_lshl_add_u64 v[4:5], v[100:101], 1, s[0:1]
	v_lshl_add_u64 v[4:5], v[4:5], 0, v[104:105]
	s_waitcnt lgkmcnt(0)
	global_store_dwordx4 v[4:5], v[0:3], off
	s_nop 1
	v_add_u32_e32 v0, v127, v133
	ds_read_b128 v[0:3], v0 offset:6144
	v_lshl_add_u64 v[4:5], v[102:103], 1, s[0:1]
	v_lshl_add_u64 v[4:5], v[4:5], 0, v[104:105]
	s_waitcnt lgkmcnt(0)
	global_store_dwordx4 v[4:5], v[0:3], off
	s_cbranch_vccnz .LBB0_636
; __device__ __forceinline__ unsigned cvt_pk_bf16(float lo, float hi) { unsigned r; asm volatile("v_cvt_pk_bf16_f32 %0, %1, %2" : "=v"(r) : "v"(lo), "v"(hi)); return r; }
; #define LAS __attribute__((address_space(3)))
; __device__ __forceinline__ int crow16(int r, int hi) { return (r & 3) + 8 * (r >> 2) + 4 * hi; }
; __device__ __forceinline__ void gla_prep_phase(const Ctx& c, int j, LAS unsigned char* lds) {
;     ...
;         if (wid < 4) {
;             const int ib = wid & 1, sb = wid >> 1; f32x16 acc = {};
; #pragma unroll 4
;             for (int ks = 0; ks < 16; ++ks) {
;                 const bf16x8 a = *(const LAS bf16x8*)(QL + (32 * ib + r32) * 528 + (ks * 16 + hi * 8) * 2);
;                 const bf16x8 bb = *(const LAS bf16x8*)(KL + (32 * sb + r32) * 528 + (ks * 16 + hi * 8) * 2);
;                 acc = __builtin_amdgcn_mfma_f32_32x32x16_bf16(a, bb, acc, 0, 0, 0); }
;             bf16_t* pdst = PM + tile * (64 * 64);
; #pragma unroll
;             for (int r = 0; r < 16; ++r) { const int i = 32 * ib + crow16(r, hi), s = 32 * sb + r32;
;                 const bool keep = (dir == 0) ? (s <= i) : (s > i);
;                 pdst[i * 64 + s] = (bf16_t)(pg8::cvt_pk_bf16(keep ? acc[r] : 0.f, 0.f) & 0xffffu); }
	ds_read_b128 v[150:153], v137
	ds_read_b128 v[154:157], v136
	ds_read_b128 v[222:225], v137 offset:32
	ds_read_b128 v[226:229], v136 offset:32
	ds_read_b128 v[230:233], v137 offset:64
	ds_read_b128 v[234:237], v136 offset:64
	ds_read_b128 v[238:241], v137 offset:96
	ds_read_b128 v[242:245], v136 offset:96
	ds_read_b128 v[246:249], v137 offset:128
	ds_read_b128 v[250:253], v136 offset:128
	s_waitcnt lgkmcnt(8)
	v_mfma_f32_32x32x16_bf16 v[0:15], v[150:153], v[154:157], 0
	ds_read_b128 v[150:153], v137 offset:160
	ds_read_b128 v[154:157], v136 offset:160
	s_waitcnt lgkmcnt(8)
	v_mfma_f32_32x32x16_bf16 v[0:15], v[222:225], v[226:229], v[0:15]
	ds_read_b128 v[222:225], v137 offset:192
	ds_read_b128 v[226:229], v136 offset:192
	s_waitcnt lgkmcnt(8)
	v_mfma_f32_32x32x16_bf16 v[0:15], v[230:233], v[234:237], v[0:15]
	ds_read_b128 v[230:233], v137 offset:224
	ds_read_b128 v[234:237], v136 offset:224
	s_waitcnt lgkmcnt(8)
	v_mfma_f32_32x32x16_bf16 v[0:15], v[238:241], v[242:245], v[0:15]
	ds_read_b128 v[238:241], v137 offset:256
	ds_read_b128 v[242:245], v136 offset:256
	s_waitcnt lgkmcnt(8)
	v_mfma_f32_32x32x16_bf16 v[0:15], v[246:249], v[250:253], v[0:15]
	ds_read_b128 v[246:249], v137 offset:288
	ds_read_b128 v[250:253], v136 offset:288
	s_waitcnt lgkmcnt(8)
	v_mfma_f32_32x32x16_bf16 v[0:15], v[150:153], v[154:157], v[0:15]
	ds_read_b128 v[150:153], v137 offset:320
	ds_read_b128 v[154:157], v136 offset:320
	s_waitcnt lgkmcnt(8)
	v_mfma_f32_32x32x16_bf16 v[0:15], v[222:225], v[226:229], v[0:15]
	ds_read_b128 v[222:225], v137 offset:352
	ds_read_b128 v[226:229], v136 offset:352
	s_waitcnt lgkmcnt(8)
	v_mfma_f32_32x32x16_bf16 v[0:15], v[230:233], v[234:237], v[0:15]
	ds_read_b128 v[230:233], v137 offset:384
	ds_read_b128 v[234:237], v136 offset:384
	s_waitcnt lgkmcnt(8)
	v_mfma_f32_32x32x16_bf16 v[0:15], v[238:241], v[242:245], v[0:15]
	ds_read_b128 v[238:241], v137 offset:416
	ds_read_b128 v[242:245], v136 offset:416
	s_waitcnt lgkmcnt(8)
	v_mfma_f32_32x32x16_bf16 v[0:15], v[246:249], v[250:253], v[0:15]
	ds_read_b128 v[246:249], v137 offset:448
	ds_read_b128 v[250:253], v136 offset:448
	s_waitcnt lgkmcnt(8)
	v_mfma_f32_32x32x16_bf16 v[0:15], v[150:153], v[154:157], v[0:15]
	ds_read_b128 v[150:153], v137 offset:480
	ds_read_b128 v[154:157], v136 offset:480
	s_waitcnt lgkmcnt(8)
	v_mfma_f32_32x32x16_bf16 v[0:15], v[222:225], v[226:229], v[0:15]
	s_waitcnt lgkmcnt(6)
	v_mfma_f32_32x32x16_bf16 v[0:15], v[230:233], v[234:237], v[0:15]
	s_waitcnt lgkmcnt(4)
	v_mfma_f32_32x32x16_bf16 v[0:15], v[238:241], v[242:245], v[0:15]
	s_waitcnt lgkmcnt(2)
	v_mfma_f32_32x32x16_bf16 v[0:15], v[246:249], v[250:253], v[0:15]
	s_waitcnt lgkmcnt(0)
	v_mfma_f32_32x32x16_bf16 v[0:15], v[150:153], v[154:157], v[0:15]
	s_nop 0
	s_lshl_b64 s[0:1], s[94:95], 13
	s_add_u32 s0, s64, s0
	s_addc_u32 s1, s65, s1
	s_xor_b64 vcc, s[66:67], s[54:55]
	v_readlane_b32 s12, v254, 30
	s_nop 5
	v_cndmask_b32_e32 v0, 0, v0, vcc
	v_readlane_b32 s13, v254, 31
	v_cvt_pk_bf16_f32 v0, v0, v16
	v_lshl_add_u64 v[150:151], v[54:55], 1, s[0:1]
	s_xor_b64 vcc, s[12:13], s[54:55]
	v_readlane_b32 s12, v254, 38
	global_store_short v[150:151], v0, off
	v_cndmask_b32_e32 v0, 0, v1, vcc
	v_readlane_b32 s13, v254, 39
	v_cvt_pk_bf16_f32 v105, v0, v16
	v_lshl_add_u64 v[0:1], v[56:57], 1, s[0:1]
	s_xor_b64 vcc, s[12:13], s[54:55]
	v_readlane_b32 s12, v254, 40
	global_store_short v[0:1], v105, off
	v_cndmask_b32_e32 v0, 0, v2, vcc
	v_readlane_b32 s13, v254, 41
	v_cvt_pk_bf16_f32 v2, v0, v16
	v_lshl_add_u64 v[0:1], v[58:59], 1, s[0:1]
	s_xor_b64 vcc, s[12:13], s[54:55]
	v_readlane_b32 s12, v254, 42
	global_store_short v[0:1], v2, off
	v_cndmask_b32_e32 v0, 0, v3, vcc
	v_readlane_b32 s13, v254, 43
	v_cvt_pk_bf16_f32 v2, v0, v16
	v_lshl_add_u64 v[0:1], v[60:61], 1, s[0:1]
	s_xor_b64 vcc, s[12:13], s[54:55]
	v_readlane_b32 s12, v254, 44
	global_store_short v[0:1], v2, off
	v_cndmask_b32_e32 v0, 0, v4, vcc
	v_readlane_b32 s13, v254, 45
	v_cvt_pk_bf16_f32 v2, v0, v16
	v_lshl_add_u64 v[0:1], v[62:63], 1, s[0:1]
	s_xor_b64 vcc, s[12:13], s[54:55]
	global_store_short v[0:1], v2, off
	v_cndmask_b32_e32 v0, 0, v5, vcc
	v_cvt_pk_bf16_f32 v2, v0, v16
	v_lshl_add_u64 v[0:1], v[64:65], 1, s[0:1]
	s_xor_b64 vcc, s[14:15], s[54:55]
	global_store_short v[0:1], v2, off
	v_cndmask_b32_e32 v0, 0, v6, vcc
	v_cvt_pk_bf16_f32 v2, v0, v16
	v_lshl_add_u64 v[0:1], v[66:67], 1, s[0:1]
	s_xor_b64 vcc, s[16:17], s[54:55]
	global_store_short v[0:1], v2, off
	v_cndmask_b32_e32 v0, 0, v7, vcc
	v_cvt_pk_bf16_f32 v2, v0, v16
	v_lshl_add_u64 v[0:1], v[68:69], 1, s[0:1]
	s_xor_b64 vcc, s[18:19], s[54:55]
	global_store_short v[0:1], v2, off
	v_cndmask_b32_e32 v0, 0, v8, vcc
	v_cvt_pk_bf16_f32 v2, v0, v16
	v_lshl_add_u64 v[0:1], v[70:71], 1, s[0:1]
	s_xor_b64 vcc, s[20:21], s[54:55]
	global_store_short v[0:1], v2, off
	v_cndmask_b32_e32 v0, 0, v9, vcc
	v_cvt_pk_bf16_f32 v2, v0, v16
	v_lshl_add_u64 v[0:1], v[72:73], 1, s[0:1]
	s_xor_b64 vcc, s[22:23], s[54:55]
	global_store_short v[0:1], v2, off
	v_cndmask_b32_e32 v0, 0, v10, vcc
	v_cvt_pk_bf16_f32 v2, v0, v16
	v_lshl_add_u64 v[0:1], v[74:75], 1, s[0:1]
	s_xor_b64 vcc, s[24:25], s[54:55]
	global_store_short v[0:1], v2, off
	v_cndmask_b32_e32 v0, 0, v11, vcc
	v_cvt_pk_bf16_f32 v2, v0, v16
	v_lshl_add_u64 v[0:1], v[76:77], 1, s[0:1]
	s_xor_b64 vcc, s[26:27], s[54:55]
	global_store_short v[0:1], v2, off
	v_cndmask_b32_e32 v0, 0, v12, vcc
	v_cvt_pk_bf16_f32 v2, v0, v16
	v_lshl_add_u64 v[0:1], v[78:79], 1, s[0:1]
	s_xor_b64 vcc, s[28:29], s[54:55]
	global_store_short v[0:1], v2, off
	v_cndmask_b32_e32 v0, 0, v13, vcc
	v_cvt_pk_bf16_f32 v2, v0, v16
	v_lshl_add_u64 v[0:1], v[80:81], 1, s[0:1]
	s_xor_b64 vcc, s[30:31], s[54:55]
	global_store_short v[0:1], v2, off
	v_cndmask_b32_e32 v0, 0, v14, vcc
	v_cvt_pk_bf16_f32 v2, v0, v16
	v_lshl_add_u64 v[0:1], v[82:83], 1, s[0:1]
	s_xor_b64 vcc, s[34:35], s[54:55]
	global_store_short v[0:1], v2, off
	v_cndmask_b32_e32 v0, 0, v15, vcc
	v_cvt_pk_bf16_f32 v2, v0, v16
	v_lshl_add_u64 v[0:1], v[84:85], 1, s[0:1]
	global_store_short v[0:1], v2, off
	s_branch .LBB0_636

; __device__ __forceinline__ void xcd_barrier(const XcdBarrier& b) {
;     ...
;     __syncthreads();
.LBB0_737:
	s_or_b64 exec, exec, s[2:3]
	s_waitcnt lgkmcnt(0)
	s_barrier
	s_nop 0
	s_nop 0
	s_nop 0
	s_nop 0
	s_nop 0
	s_nop 0
	s_nop 0
	s_nop 0
	s_nop 0
	s_nop 0

; __device__ __forceinline__ unsigned cvt_pk_bf16(float lo, float hi) { unsigned r; asm volatile("v_cvt_pk_bf16_f32 %0, %1, %2" : "=v"(r) : "v"(lo), "v"(hi)); return r; }
; #define LAS __attribute__((address_space(3)))
; __device__ __forceinline__ int crow16(int r, int hi) { return (r & 3) + 8 * (r >> 2) + 4 * hi; }
; __device__ __forceinline__ void gla_prep_phase(const Ctx& c, int j, LAS unsigned char* lds) {
;     ...
; #pragma unroll
;         for (int jj = 0; jj < 4; ++jj) { const int idx = c.tid + 512 * jj, i = idx >> 5, c16 = idx & 31;
;             *(u32x4*)(qdst + i * 256 + c16 * 8) = *(const LAS u32x4*)(QL + i * 528 + c16 * 16); }
;         if (wid < 4) {
;             const int ib = wid & 1, sb = wid >> 1; f32x16 acc = {};
; #pragma unroll 4
;             for (int ks = 0; ks < 16; ++ks) {
;                 const bf16x8 a = *(const LAS bf16x8*)(QL + (32 * ib + r32) * 528 + (ks * 16 + hi * 8) * 2);
;                 const bf16x8 bb = *(const LAS bf16x8*)(KL + (32 * sb + r32) * 528 + (ks * 16 + hi * 8) * 2);
;                 acc = __builtin_amdgcn_mfma_f32_32x32x16_bf16(a, bb, acc, 0, 0, 0); }
;             bf16_t* pdst = PM + tile * (64 * 64);
; #pragma unroll
;             for (int r = 0; r < 16; ++r) { const int i = 32 * ib + crow16(r, hi), s = 32 * sb + r32;
;                 const bool keep = (dir == 0) ? (s <= i) : (s > i);
;                 pdst[i * 64 + s] = (bf16_t)(pg8::cvt_pk_bf16(keep ? acc[r] : 0.f, 0.f) & 0xffffu); }
.LBB0_1634:
	s_or_b64 exec, exec, s[0:1]
	s_lshl_b64 s[0:1], s[66:67], 14
	v_add_u32_e32 v0, v121, v133
	s_lshl_b64 s[0:1], s[0:1], 1
	s_waitcnt lgkmcnt(0)
	s_barrier
	ds_read_b128 v[0:3], v0 offset:6144
	s_add_u32 s0, s97, s0
	s_addc_u32 s1, s77, s1
	v_lshl_add_u64 v[4:5], v[96:97], 1, s[0:1]
	v_mov_b32_e32 v105, v16
	v_lshl_add_u64 v[4:5], v[4:5], 0, v[104:105]
	s_waitcnt lgkmcnt(0)
	global_store_dwordx4 v[4:5], v[0:3], off
	v_lshl_add_u64 v[4:5], v[98:99], 1, s[0:1]
	v_lshl_add_u64 v[4:5], v[4:5], 0, v[104:105]
	v_add_u32_e32 v0, v123, v133
	ds_read_b128 v[0:3], v0 offset:6144
	s_andn2_b64 vcc, exec, s[62:63]
	s_waitcnt lgkmcnt(0)
	global_store_dwordx4 v[4:5], v[0:3], off
	s_nop 1
	v_add_u32_e32 v0, v125, v133
	ds_read_b128 v[0:3], v0 offset:6144
	v_lshl_add_u64 v[4:5], v[100:101], 1, s[0:1]
	v_lshl_add_u64 v[4:5], v[4:5], 0, v[104:105]
	s_waitcnt lgkmcnt(0)
	global_store_dwordx4 v[4:5], v[0:3], off
	s_nop 1
	v_add_u32_e32 v0, v127, v133
	ds_read_b128 v[0:3], v0 offset:6144
	v_lshl_add_u64 v[4:5], v[102:103], 1, s[0:1]
	v_lshl_add_u64 v[4:5], v[4:5], 0, v[104:105]
	s_waitcnt lgkmcnt(0)
	global_store_dwordx4 v[4:5], v[0:3], off
	s_cbranch_vccnz .LBB0_1592
	ds_read_b128 v[150:153], v137
	ds_read_b128 v[154:157], v136
	ds_read_b128 v[222:225], v137 offset:32
	ds_read_b128 v[226:229], v136 offset:32
	ds_read_b128 v[230:233], v137 offset:64
	ds_read_b128 v[234:237], v136 offset:64
	ds_read_b128 v[238:241], v137 offset:96
	ds_read_b128 v[242:245], v136 offset:96
	ds_read_b128 v[246:249], v137 offset:128
	ds_read_b128 v[250:253], v136 offset:128
	s_waitcnt lgkmcnt(8)
	v_mfma_f32_32x32x16_bf16 v[0:15], v[150:153], v[154:157], 0
	ds_read_b128 v[150:153], v137 offset:160
	ds_read_b128 v[154:157], v136 offset:160
	s_waitcnt lgkmcnt(8)
	v_mfma_f32_32x32x16_bf16 v[0:15], v[222:225], v[226:229], v[0:15]
	ds_read_b128 v[222:225], v137 offset:192
	ds_read_b128 v[226:229], v136 offset:192
	s_waitcnt lgkmcnt(8)
	v_mfma_f32_32x32x16_bf16 v[0:15], v[230:233], v[234:237], v[0:15]
	ds_read_b128 v[230:233], v137 offset:224
	ds_read_b128 v[234:237], v136 offset:224
	s_waitcnt lgkmcnt(8)
	v_mfma_f32_32x32x16_bf16 v[0:15], v[238:241], v[242:245], v[0:15]
	ds_read_b128 v[238:241], v137 offset:256
	ds_read_b128 v[242:245], v136 offset:256
	s_waitcnt lgkmcnt(8)
	v_mfma_f32_32x32x16_bf16 v[0:15], v[246:249], v[250:253], v[0:15]
	ds_read_b128 v[246:249], v137 offset:288
	ds_read_b128 v[250:253], v136 offset:288
	s_waitcnt lgkmcnt(8)
	v_mfma_f32_32x32x16_bf16 v[0:15], v[150:153], v[154:157], v[0:15]
	ds_read_b128 v[150:153], v137 offset:320
	ds_read_b128 v[154:157], v136 offset:320
	s_waitcnt lgkmcnt(8)
	v_mfma_f32_32x32x16_bf16 v[0:15], v[222:225], v[226:229], v[0:15]
	ds_read_b128 v[222:225], v137 offset:352
	ds_read_b128 v[226:229], v136 offset:352
	s_waitcnt lgkmcnt(8)
	v_mfma_f32_32x32x16_bf16 v[0:15], v[230:233], v[234:237], v[0:15]
	ds_read_b128 v[230:233], v137 offset:384
	ds_read_b128 v[234:237], v136 offset:384
	s_waitcnt lgkmcnt(8)
	v_mfma_f32_32x32x16_bf16 v[0:15], v[238:241], v[242:245], v[0:15]
	ds_read_b128 v[238:241], v137 offset:416
	ds_read_b128 v[242:245], v136 offset:416
	s_waitcnt lgkmcnt(8)
	v_mfma_f32_32x32x16_bf16 v[0:15], v[246:249], v[250:253], v[0:15]
	ds_read_b128 v[246:249], v137 offset:448
	ds_read_b128 v[250:253], v136 offset:448
	s_waitcnt lgkmcnt(8)
	v_mfma_f32_32x32x16_bf16 v[0:15], v[150:153], v[154:157], v[0:15]
	ds_read_b128 v[150:153], v137 offset:480
	ds_read_b128 v[154:157], v136 offset:480
	s_waitcnt lgkmcnt(8)
	v_mfma_f32_32x32x16_bf16 v[0:15], v[222:225], v[226:229], v[0:15]
	s_waitcnt lgkmcnt(6)
	v_mfma_f32_32x32x16_bf16 v[0:15], v[230:233], v[234:237], v[0:15]
	s_waitcnt lgkmcnt(4)
	v_mfma_f32_32x32x16_bf16 v[0:15], v[238:241], v[242:245], v[0:15]
	s_waitcnt lgkmcnt(2)
	v_mfma_f32_32x32x16_bf16 v[0:15], v[246:249], v[250:253], v[0:15]
	s_waitcnt lgkmcnt(0)
	v_mfma_f32_32x32x16_bf16 v[0:15], v[150:153], v[154:157], v[0:15]
	s_nop 0
	s_lshl_b64 s[0:1], s[66:67], 13
	v_readlane_b32 s33, v254, 40
	s_add_u32 s0, s33, s0
	s_addc_u32 s1, s78, s1
	s_xor_b64 vcc, s[2:3], s[54:55]
	s_nop 5
	v_cndmask_b32_e32 v0, 0, v0, vcc
	v_cvt_pk_bf16_f32 v0, v0, v16
	v_lshl_add_u64 v[150:151], v[54:55], 1, s[0:1]
	s_xor_b64 vcc, s[4:5], s[54:55]
	global_store_short v[150:151], v0, off
	v_cndmask_b32_e32 v0, 0, v1, vcc
	v_cvt_pk_bf16_f32 v105, v0, v16
	v_lshl_add_u64 v[0:1], v[56:57], 1, s[0:1]
	s_xor_b64 vcc, s[6:7], s[54:55]
	global_store_short v[0:1], v105, off
	v_cndmask_b32_e32 v0, 0, v2, vcc
	v_cvt_pk_bf16_f32 v2, v0, v16
	v_lshl_add_u64 v[0:1], v[58:59], 1, s[0:1]
	s_xor_b64 vcc, s[8:9], s[54:55]
	global_store_short v[0:1], v2, off
	v_cndmask_b32_e32 v0, 0, v3, vcc
	v_cvt_pk_bf16_f32 v2, v0, v16
	v_lshl_add_u64 v[0:1], v[60:61], 1, s[0:1]
	s_xor_b64 vcc, s[10:11], s[54:55]
	global_store_short v[0:1], v2, off
	v_cndmask_b32_e32 v0, 0, v4, vcc
	v_cvt_pk_bf16_f32 v2, v0, v16
	v_lshl_add_u64 v[0:1], v[62:63], 1, s[0:1]
	s_xor_b64 vcc, s[12:13], s[54:55]
	global_store_short v[0:1], v2, off
	v_cndmask_b32_e32 v0, 0, v5, vcc
	v_cvt_pk_bf16_f32 v2, v0, v16
	v_lshl_add_u64 v[0:1], v[64:65], 1, s[0:1]
	s_xor_b64 vcc, s[14:15], s[54:55]
	global_store_short v[0:1], v2, off
	v_cndmask_b32_e32 v0, 0, v6, vcc
	v_cvt_pk_bf16_f32 v2, v0, v16
	v_lshl_add_u64 v[0:1], v[66:67], 1, s[0:1]
	s_xor_b64 vcc, s[16:17], s[54:55]
	global_store_short v[0:1], v2, off
	v_cndmask_b32_e32 v0, 0, v7, vcc
	v_cvt_pk_bf16_f32 v2, v0, v16
	v_lshl_add_u64 v[0:1], v[68:69], 1, s[0:1]
	s_xor_b64 vcc, s[18:19], s[54:55]
	global_store_short v[0:1], v2, off
	v_cndmask_b32_e32 v0, 0, v8, vcc
	v_cvt_pk_bf16_f32 v2, v0, v16
	v_lshl_add_u64 v[0:1], v[70:71], 1, s[0:1]
	s_xor_b64 vcc, s[20:21], s[54:55]
	global_store_short v[0:1], v2, off
	v_cndmask_b32_e32 v0, 0, v9, vcc
	v_cvt_pk_bf16_f32 v2, v0, v16
	v_lshl_add_u64 v[0:1], v[72:73], 1, s[0:1]
	s_xor_b64 vcc, s[22:23], s[54:55]
	global_store_short v[0:1], v2, off
	v_cndmask_b32_e32 v0, 0, v10, vcc
	v_cvt_pk_bf16_f32 v2, v0, v16
	v_lshl_add_u64 v[0:1], v[74:75], 1, s[0:1]
	s_xor_b64 vcc, s[24:25], s[54:55]
	global_store_short v[0:1], v2, off
	v_cndmask_b32_e32 v0, 0, v11, vcc
	v_cvt_pk_bf16_f32 v2, v0, v16
	v_lshl_add_u64 v[0:1], v[76:77], 1, s[0:1]
	s_xor_b64 vcc, s[26:27], s[54:55]
	global_store_short v[0:1], v2, off
	v_cndmask_b32_e32 v0, 0, v12, vcc
	v_cvt_pk_bf16_f32 v2, v0, v16
	v_lshl_add_u64 v[0:1], v[78:79], 1, s[0:1]
	s_xor_b64 vcc, s[28:29], s[54:55]
	global_store_short v[0:1], v2, off
	v_cndmask_b32_e32 v0, 0, v13, vcc
	v_cvt_pk_bf16_f32 v2, v0, v16
	v_lshl_add_u64 v[0:1], v[80:81], 1, s[0:1]
	s_xor_b64 vcc, s[30:31], s[54:55]
	global_store_short v[0:1], v2, off
	v_cndmask_b32_e32 v0, 0, v14, vcc
	v_cvt_pk_bf16_f32 v2, v0, v16
	v_lshl_add_u64 v[0:1], v[82:83], 1, s[0:1]
	s_xor_b64 vcc, s[34:35], s[54:55]
	global_store_short v[0:1], v2, off
	v_cndmask_b32_e32 v0, 0, v15, vcc
	v_cvt_pk_bf16_f32 v2, v0, v16
	v_lshl_add_u64 v[0:1], v[84:85], 1, s[0:1]
	global_store_short v[0:1], v2, off
	s_branch .LBB0_1592
